# attention key loops: the first QK step's four K fragment reads issued together behind counted lgkmcnt waits (one exposed LDS latency instead of three)
# baseline (speedup 1.0000x reference)
; #define LAS __attribute__((address_space(3)))
; #define AT_LOAD(t) do { const GAS u32x4* Kg_ = (const GAS u32x4*)(Kp + (size_t)(t) * 128 * DK); const GAS u32x4* Vg_ = (const GAS u32x4*)(Vp + (size_t)(t) * 128 * 64); \
;         _Pragma("unroll") for (int i_ = 0; i_ < NKC; ++i_) kreg[i_] = Kg_[tid + 512 * i_]; vreg[0] = Vg_[tid]; vreg[1] = Vg_[tid + 512]; } while (0)
; #define AT_STORE(bf_) do { LAS unsigned char* nb_ = lds + (bf_) * AT_KBUF; _Pragma("unroll") for (int i_ = 0; i_ < NKC; ++i_) *(LAS u32x4*)(nb_ + koff[i_]) = kreg[i_]; \
;         *(LAS u32x4*)(lds + (bf_) * AT_VBUF + voff[0]) = vreg[0]; *(LAS u32x4*)(lds + (bf_) * AT_VBUF + voff[1]) = vreg[1]; } while (0)
; template <int DK>
; __device__ __forceinline__ void attn_unit(LAS unsigned char* lds, const GAS bf16* Qp, const GAS bf16* Kp, const GAS bf16* Vp, GAS bf16* Yp, int b, int j, int nkeys, int tid, int lane, int wave) {
;     ...
;         { LAS unsigned char* kb = lds + cur * AT_KBUF + kfo;
;           bf16x8 ka[2][4];
; #pragma unroll
;           for (int q4 = 0; q4 < 4; ++q4) ka[0][q4] = *(LAS bf16x8*)(kb + q4 * 32 * KSTR);
; #pragma unroll
;           for (int d0 = 0; d0 < ND; ++d0) {
;               if (d0 + 1 < ND) {
; #pragma unroll
;                   for (int q4 = 0; q4 < 4; ++q4) ka[(d0 + 1) & 1][q4] = *(LAS bf16x8*)(kb + q4 * 32 * KSTR + (d0 + 1) * 32);
;               }
; #pragma unroll
;               for (int q4 = 0; q4 < 4; ++q4) p[q4] = __builtin_amdgcn_mfma_f32_32x32x16_bf16(ka[d0 & 1][q4], qr[d0], d0 == 0 ? negm : p[q4], 0, 0, 0);
;               if (d0 == 0) { if (t + 1 < NT) AT_STORE(cur ^ 1); if (t + 2 < NT) AT_LOAD(t + 2); }
.LBB0_137:
	s_add_i32 s11, s10, -2
	s_and_b32 s11, s11, 1
	s_mul_i32 s12, s11, 0x6800
	v_add_u32_e32 v0, s12, v237
	ds_read_b128 v[6:9], v0
	ds_read_b128 v[2:5], v0 offset:32
	ds_read_b128 v[10:13], v0 offset:6656
	ds_read_b128 v[80:83], v0 offset:13312
	ds_read_b128 v[214:217], v0 offset:19968
	s_add_i32 s12, s10, -1
	s_cmp_ge_u32 s12, s8
	s_waitcnt lgkmcnt(4)
	v_mfma_f32_32x32x16_bf16 v[128:143], v[6:9], v[144:147], v[64:79]
	ds_read_b128 v[6:9], v0 offset:6688
	s_waitcnt lgkmcnt(3)
	v_mfma_f32_32x32x16_bf16 v[112:127], v[10:13], v[144:147], v[64:79]
	ds_read_b128 v[10:13], v0 offset:13344
	ds_read_b128 v[188:191], v0 offset:20000
	s_waitcnt lgkmcnt(4)
	v_mfma_f32_32x32x16_bf16 v[96:111], v[80:83], v[144:147], v[64:79]
	v_mov_b64_e32 v[94:95], v[78:79]
	v_mov_b64_e32 v[92:93], v[76:77]
	v_mov_b64_e32 v[90:91], v[74:75]
	v_mov_b64_e32 v[88:89], v[72:73]
	v_mov_b64_e32 v[86:87], v[70:71]
	v_mov_b64_e32 v[84:85], v[68:69]
	v_mov_b64_e32 v[82:83], v[66:67]
	v_mov_b64_e32 v[80:81], v[64:65]
	s_waitcnt lgkmcnt(1)
	s_nop 0
	v_mfma_f32_32x32x16_bf16 v[80:95], v[214:217], v[144:147], v[80:95]
	s_cbranch_scc1 .LBB0_139
	s_xor_b32 s12, s11, 1
	s_lshl_b32 s13, s12, 14
	s_add_i32 s13, s13, 0
	s_mulk_i32 s12, 0x2800
	v_add_u32_e32 v14, s13, v235
	s_add_i32 s13, s13, s12
	v_add_u32_e32 v15, s13, v232
	s_waitcnt vmcnt(6)
	ds_write_b128 v15, v[160:163]
	v_add_u32_e32 v15, s13, v233
	s_waitcnt vmcnt(5)
	ds_write_b128 v15, v[164:167]
	v_add_u32_e32 v15, s13, v234
	s_waitcnt vmcnt(4)
	ds_write_b128 v15, v[176:179]
	s_waitcnt vmcnt(3)
	ds_write_b128 v14, v[180:183] offset:53248
	s_waitcnt vmcnt(2)
	ds_write_b128 v14, v[184:187] offset:57344

; #define LAS __attribute__((address_space(3)))
; #define AT_LOAD(t) do { const GAS u32x4* Kg_ = (const GAS u32x4*)(Kp + (size_t)(t) * 128 * DK); const GAS u32x4* Vg_ = (const GAS u32x4*)(Vp + (size_t)(t) * 128 * 64); \
;         _Pragma("unroll") for (int i_ = 0; i_ < NKC; ++i_) kreg[i_] = Kg_[tid + 512 * i_]; vreg[0] = Vg_[tid]; vreg[1] = Vg_[tid + 512]; } while (0)
; #define AT_STORE(bf_) do { LAS unsigned char* nb_ = lds + (bf_) * AT_KBUF; _Pragma("unroll") for (int i_ = 0; i_ < NKC; ++i_) *(LAS u32x4*)(nb_ + koff[i_]) = kreg[i_]; \
;         *(LAS u32x4*)(lds + (bf_) * AT_VBUF + voff[0]) = vreg[0]; *(LAS u32x4*)(lds + (bf_) * AT_VBUF + voff[1]) = vreg[1]; } while (0)
; template <int DK>
; __device__ __forceinline__ void attn_unit(LAS unsigned char* lds, const GAS bf16* Qp, const GAS bf16* Kp, const GAS bf16* Vp, GAS bf16* Yp, int b, int j, int nkeys, int tid, int lane, int wave) {
;     ...
;         { LAS unsigned char* kb = lds + cur * AT_KBUF + kfo;
;           bf16x8 ka[2][4];
; #pragma unroll
;           for (int q4 = 0; q4 < 4; ++q4) ka[0][q4] = *(LAS bf16x8*)(kb + q4 * 32 * KSTR);
; #pragma unroll
;           for (int d0 = 0; d0 < ND; ++d0) {
;               if (d0 + 1 < ND) {
; #pragma unroll
;                   for (int q4 = 0; q4 < 4; ++q4) ka[(d0 + 1) & 1][q4] = *(LAS bf16x8*)(kb + q4 * 32 * KSTR + (d0 + 1) * 32);
;               }
; #pragma unroll
;               for (int q4 = 0; q4 < 4; ++q4) p[q4] = __builtin_amdgcn_mfma_f32_32x32x16_bf16(ka[d0 & 1][q4], qr[d0], d0 == 0 ? negm : p[q4], 0, 0, 0);
;               if (d0 == 0) { if (t + 1 < NT) AT_STORE(cur ^ 1); if (t + 2 < NT) AT_LOAD(t + 2); }
.LBB0_159:
	s_add_i32 s8, s7, -2
	s_and_b32 s8, s8, 1
	s_mul_i32 s9, s8, 0x6800
	v_add_u32_e32 v0, s9, v242
	ds_read_b128 v[66:69], v0
	ds_read_b128 v[162:165], v0 offset:32
	ds_read_b128 v[70:73], v0 offset:4608
	ds_read_b128 v[74:77], v0 offset:9216
	ds_read_b128 v[186:189], v0 offset:13824
	s_add_i32 s9, s7, -1
	s_cmp_ge_u32 s9, s4
	s_waitcnt lgkmcnt(4)
	v_mfma_f32_32x32x16_bf16 v[114:129], v[66:69], v[130:133], v[50:65]
	ds_read_b128 v[166:169], v0 offset:4640
	s_waitcnt lgkmcnt(3)
	v_mfma_f32_32x32x16_bf16 v[98:113], v[70:73], v[130:133], v[50:65]
	ds_read_b128 v[170:173], v0 offset:9248
	ds_read_b128 v[174:177], v0 offset:13856
	s_waitcnt lgkmcnt(4)
	v_mfma_f32_32x32x16_bf16 v[82:97], v[74:77], v[130:133], v[50:65]
	v_mov_b64_e32 v[80:81], v[64:65]
	v_mov_b64_e32 v[78:79], v[62:63]
	v_mov_b64_e32 v[76:77], v[60:61]
	v_mov_b64_e32 v[74:75], v[58:59]
	v_mov_b64_e32 v[72:73], v[56:57]
	v_mov_b64_e32 v[70:71], v[54:55]
	v_mov_b64_e32 v[68:69], v[52:53]
	v_mov_b64_e32 v[66:67], v[50:51]
	s_waitcnt lgkmcnt(1)
	s_nop 0
	v_mfma_f32_32x32x16_bf16 v[66:81], v[186:189], v[130:133], v[66:81]
	s_cbranch_scc1 .LBB0_161
	s_xor_b32 s9, s8, 1
	s_lshl_b32 s10, s9, 14
	s_add_i32 s10, s10, 0
	s_mulk_i32 s9, 0x2800
	v_add_u32_e32 v186, s10, v235
	s_add_i32 s10, s10, s9
	v_add_u32_e32 v187, s10, v240
	s_waitcnt vmcnt(3)
	ds_write_b128 v187, v[146:149]
	v_add_u32_e32 v187, s10, v241
	s_waitcnt vmcnt(2)
	ds_write_b128 v187, v[150:153]
	s_waitcnt vmcnt(1)
	ds_write_b128 v186, v[154:157] offset:53248
	s_waitcnt vmcnt(0)
	ds_write_b128 v186, v[158:161] offset:57344
